# P1: next tile's first fragment LDS reads issued ahead of the epilogue
# baseline (speedup 1.0000x reference)
; #define PG8_STAGE(bufoff, gbase, voff) do { _Pragma("unroll") for (int _i = 0; _i < 2; ++_i) \
;         __builtin_amdgcn_global_load_lds((const unsigned*)((const char*)(gbase) + (voff)[_i]), (PG8_LAS unsigned*)(lds + (bufoff) + ldsw + _i * 8192), 16, 0, 0); } while (0)
; #define PG8_LDA(dst, b, h) do { _Pragma("unroll") for (int m = 0; m < 4; ++m) _Pragma("unroll") for (int k = 0; k < 2; ++k) dst[m][k] = *(const PG8_LAS bf16x8*)(lds + PG8_SA(b, h) + aoff + m * 2048 + k * 1024); } while (0)
; #define PG8_LDB(dst, b, h) do { _Pragma("unroll") for (int n = 0; n < 2; ++n) _Pragma("unroll") for (int k = 0; k < 2; ++k) dst[n][k] = *(const PG8_LAS bf16x8*)(lds + PG8_SB(b, h) + boff + n * 2048 + k * 1024); } while (0)
; #define PG8_WAIT_V(n) asm volatile("s_waitcnt vmcnt(" #n ")" ::: "memory")
; #define PG8_BAR __builtin_amdgcn_s_barrier()
; #define PG8_SCHED __builtin_amdgcn_sched_barrier(0)
; template <class Epi, class Sched, bool ALIGN_EPI = false, bool SP2 = false, bool RS = false, bool BPRE = false>
; __device__ __forceinline__ void gemm_phase(PG8_LAS unsigned char* lds, const Gemm g, const Sched& S, const Epi& E, const float* rs_ss = nullptr, PG8_LAS float* rs_tab = nullptr) {
;     ...
;         PG8_WAIT_V(2); PG8_BAR;
;         PG8_STAGE(PG8_SB(1, 0), cB + kstep, voffB); PG8_STAGE(PG8_SA(1, 0), cA + kstep, voffA); PG8_STAGE(PG8_SB(1, 1), cB + hstep + kstep, voffB);
;         PG8_WAIT_V(6); PG8_BAR;
;     ...
;             PG8_LDB(B0, 0, 0); PG8_LDB(B1, 0, 1); PG8_SCHED; PG8_LDA(At, 0, 0); PG8_STAGE(PG8_SA(1, 1), a1 + hstep, voffA);
.LBB0_190:
	s_and_b32 s5, s0, 3
	s_ashr_i32 s77, s3, 31
	s_ashr_i32 s78, s2, 31
	s_lshl_b32 s12, s7, 13
	s_lshl_b32 s13, s5, 12
	s_add_u32 s0, s58, 0x4000
	s_addc_u32 s1, s59, 0
	s_add_i32 m0, s72, 0x18000
	v_lshl_add_u64 v[4:5], s[0:1], 0, v[138:139]
	s_waitcnt vmcnt(2)
	s_barrier
	global_load_lds_dwordx4 v[4:5], off
	s_add_i32 m0, s72, 0x1a000
	v_lshl_add_u64 v[4:5], s[0:1], 0, v[140:141]
	s_add_u32 s0, s56, 0x4000
	s_addc_u32 s1, s57, 0
	s_add_i32 s79, s72, 0x8000
	global_load_lds_dwordx4 v[4:5], off
	v_lshl_add_u64 v[4:5], s[0:1], 0, v[138:139]
	s_mov_b32 m0, s79
	s_add_i32 s80, s72, 0xa000
	global_load_lds_dwordx4 v[4:5], off
	v_lshl_add_u64 v[4:5], s[0:1], 0, v[140:141]
	s_add_u32 s0, s58, 0x84000
	s_mov_b32 m0, s80
	s_addc_u32 s1, s59, 0
	global_load_lds_dwordx4 v[4:5], off
	s_add_i32 m0, s72, 0x1c000
	v_lshl_add_u64 v[4:5], s[0:1], 0, v[138:139]
	global_load_lds_dwordx4 v[4:5], off
	v_lshl_add_u64 v[4:5], s[0:1], 0, v[140:141]
	s_add_i32 m0, s72, 0x1e000
	v_and_b32_e32 v6, 48, v0
	global_load_lds_dwordx4 v[4:5], off
	v_lshlrev_b32_e32 v1, 6, v0
	s_movk_i32 s0, 0x3c0
	v_and_b32_e32 v4, 15, v0
	v_and_or_b32 v7, v1, s0, v6
	v_lshlrev_b32_e32 v1, 2, v0
	v_bfe_u32 v5, v0, 4, 2
	v_and_b32_e32 v8, 32, v1
	v_lshl_or_b32 v1, s7, 6, v4
	v_lshlrev_b32_e32 v4, 6, v4
	v_or_b32_e32 v6, v4, v6
	s_waitcnt vmcnt(6)
	s_cmpk_lt_u32 s6, 0x100
	v_lshl_or_b32 v4, v5, 4, v4
	v_cmp_eq_u32_e64 s[0:1], 0, v5
	v_bitop3_b32 v6, v6, s12, v8 bitop3:0xde
	v_bitop3_b32 v160, s13, v7, v8 bitop3:0xf6
	s_cselect_b64 s[12:13], -1, 0
	s_lshl_b32 s6, s5, 1
	v_lshl_or_b32 v4, s5, 10, v4
	v_mov_b32_e32 v5, v142
	v_add_u32_e32 v146, v2, v3
	s_add_i32 s83, 0, 0x10000
	s_add_i32 s86, 0, 0x14000
	v_mbcnt_lo_u32_b32 v2, -1, 0
	s_or_b32 s81, s6, 0xffffffa0
	v_lshl_add_u64 v[144:145], s[36:37], 0, v[4:5]
	v_mov_b32_e32 v147, v142
	v_mov_b64_e32 v[148:149], 0x700
	v_mov_b64_e32 v[150:151], 0x6ff
	s_movk_i32 s82, 0xe1
	v_add_u32_e32 v161, s83, v160
	v_add_u32_e32 v162, s86, v160
	v_add_u32_e32 v163, 0, v6
	s_mov_b32 s14, 0x3db8aa3b
	v_mbcnt_hi_u32_b32 v164, -1, v2
	s_barrier
	ds_read_b128 v[130:133], v161
	ds_read_b128 v[134:137], v161 offset:1024
	ds_read_b128 v[152:155], v161 offset:2048
	ds_read_b128 v[156:159], v161 offset:3072
	ds_read_b128 v[166:169], v162
	ds_read_b128 v[170:173], v162 offset:1024
	ds_read_b128 v[174:177], v162 offset:2048
	ds_read_b128 v[182:185], v162 offset:3072
	ds_read_b128 v[186:189], v163
	ds_read_b128 v[190:193], v163 offset:1024
	ds_read_b128 v[194:197], v163 offset:2048
	ds_read_b128 v[198:201], v163 offset:3072
	ds_read_b128 v[202:205], v163 offset:4096
	ds_read_b128 v[206:209], v163 offset:5120
	ds_read_b128 v[210:213], v163 offset:6144
	ds_read_b128 v[214:217], v163 offset:7168
	s_branch .LBB0_193

; #define PG8_STAGE(bufoff, gbase, voff) do { _Pragma("unroll") for (int _i = 0; _i < 2; ++_i) \
;         __builtin_amdgcn_global_load_lds((const unsigned*)((const char*)(gbase) + (voff)[_i]), (PG8_LAS unsigned*)(lds + (bufoff) + ldsw + _i * 8192), 16, 0, 0); } while (0)
; #define PG8_LDA(dst, b, h) do { _Pragma("unroll") for (int m = 0; m < 4; ++m) _Pragma("unroll") for (int k = 0; k < 2; ++k) dst[m][k] = *(const PG8_LAS bf16x8*)(lds + PG8_SA(b, h) + aoff + m * 2048 + k * 1024); } while (0)
; #define PG8_LDB(dst, b, h) do { _Pragma("unroll") for (int n = 0; n < 2; ++n) _Pragma("unroll") for (int k = 0; k < 2; ++k) dst[n][k] = *(const PG8_LAS bf16x8*)(lds + PG8_SB(b, h) + boff + n * 2048 + k * 1024); } while (0)
; #define PG8_MMA(ai, bj, At, Bt) do { __builtin_amdgcn_s_setprio(1); _Pragma("unroll") for (int m = 0; m < 4; ++m) _Pragma("unroll") for (int n = 0; n < 2; ++n) _Pragma("unroll") for (int k = 0; k < 2; ++k) \
;         acc[ai][bj][m][n] = __builtin_amdgcn_mfma_f32_16x16x32_bf16(Bt[n][k], At[m][k], acc[ai][bj][m][n], 0, 0, 0); __builtin_amdgcn_s_setprio(0); } while (0)
; #define PG8_WAIT_V(n) asm volatile("s_waitcnt vmcnt(" #n ")" ::: "memory")
; #define PG8_WAIT_L(n) asm volatile("s_waitcnt lgkmcnt(" #n ")" ::: "memory")
; #define PG8_BAR __builtin_amdgcn_s_barrier()
; #define PG8_SCHED __builtin_amdgcn_sched_barrier(0)
; template <class Epi, class Sched, bool ALIGN_EPI = false, bool SP2 = false, bool RS = false, bool BPRE = false>
; __device__ __forceinline__ void gemm_phase(PG8_LAS unsigned char* lds, const Gemm g, const Sched& S, const Epi& E, const float* rs_ss = nullptr, PG8_LAS float* rs_tab = nullptr) {
;     ...
;         const bool has_next = S.next(ui + 1, nxt);
;         const char* nA = has_next ? (const char*)g.A + (size_t)nxt.pm * tstep : cA; const char* nB = has_next ? (const char*)g.Bt + (size_t)nxt.pn * tstep : cB;
;     ...
;             PG8_LDB(B0, 0, 0); PG8_LDB(B1, 0, 1); PG8_SCHED; PG8_LDA(At, 0, 0); PG8_STAGE(PG8_SA(1, 1), a1 + hstep, voffA);
;             PG8_WAIT_V(8); PG8_WAIT_L(0); PG8_BAR; PG8_MMA(0, 0, At, B0); PG8_MMA(0, 1, At, B1); PG8_BAR; PG8_SCHED;
;             PG8_LDA(At, 0, 1); PG8_STAGE(PG8_SB(0, 0), b2, voffB); PG8_STAGE(PG8_SB(0, 1), b2 + hstep, voffB); PG8_STAGE(PG8_SA(0, 0), a2, voffA);
;             PG8_WAIT_V(8); PG8_WAIT_L(0); PG8_BAR; PG8_MMA(1, 0, At, B0); PG8_MMA(1, 1, At, B1); PG8_BAR; PG8_SCHED;
.LBB0_195:
	s_ashr_i32 s19, s18, 31
	s_lshl_b64 s[20:21], s[18:19], 20
	s_add_u32 s20, s30, s20
	s_addc_u32 s21, s31, s21
	s_and_b64 s[44:45], s[6:7], exec
	s_cselect_b32 s5, s21, s57
	s_cselect_b32 s19, s20, s56
	s_ashr_i32 s17, s16, 31
	s_lshl_b64 s[44:45], s[16:17], 20
	s_add_u32 s44, s24, s44
	s_addc_u32 s45, s25, s45
	s_and_b64 s[60:61], s[6:7], exec
	s_cselect_b32 s17, s45, s59
	s_cselect_b32 s47, s44, s58
	s_add_u32 s56, s56, 0x84000
	s_addc_u32 s57, s57, 0
	s_add_u32 s87, s58, 0x8000
	s_addc_u32 s88, s59, 0
	s_mov_b32 s89, -2
	s_waitcnt lgkmcnt(0)
	s_add_u32 s58, s56, 0xfff84000
	s_addc_u32 s59, s57, -1
	s_cmp_eq_u32 s89, 28
	s_cselect_b32 s70, s19, s58
	s_cselect_b32 s71, s5, s59
	s_cselect_b32 s60, s47, s87
	s_cselect_b32 s61, s17, s88
	s_add_u32 s58, s70, 0x4000
	s_addc_u32 s59, s71, 0
	v_lshl_add_u64 v[178:179], s[56:57], 0, v[138:139]
	s_add_i32 m0, s72, 0xc000
	global_load_lds_dwordx4 v[178:179], off
	v_lshl_add_u64 v[178:179], s[56:57], 0, v[146:147]
	s_add_i32 m0, s72, 0xe000
	s_nop 0
	global_load_lds_dwordx4 v[178:179], off
	s_waitcnt vmcnt(8)
	s_waitcnt lgkmcnt(0)
	s_barrier
	s_setprio 1
	s_waitcnt lgkmcnt(0)
	v_mfma_f32_16x16x32_bf16 v[126:129], v[130:133], v[186:189], 0
	v_mfma_f32_16x16x32_bf16 v[122:125], v[152:155], v[186:189], 0
	v_mfma_f32_16x16x32_bf16 v[110:113], v[130:133], v[194:197], 0
	v_mfma_f32_16x16x32_bf16 v[106:109], v[152:155], v[194:197], 0
	v_mfma_f32_16x16x32_bf16 v[94:97], v[130:133], v[202:205], 0
	v_mfma_f32_16x16x32_bf16 v[90:93], v[152:155], v[202:205], 0
	v_mfma_f32_16x16x32_bf16 v[78:81], v[130:133], v[210:213], 0
	v_mfma_f32_16x16x32_bf16 v[74:77], v[152:155], v[210:213], 0
	v_mfma_f32_16x16x32_bf16 v[126:129], v[134:137], v[190:193], v[126:129]
	v_mfma_f32_16x16x32_bf16 v[122:125], v[156:159], v[190:193], v[122:125]
	v_mfma_f32_16x16x32_bf16 v[110:113], v[134:137], v[198:201], v[110:113]
	v_mfma_f32_16x16x32_bf16 v[106:109], v[156:159], v[198:201], v[106:109]
	v_mfma_f32_16x16x32_bf16 v[94:97], v[134:137], v[206:209], v[94:97]
	v_mfma_f32_16x16x32_bf16 v[90:93], v[156:159], v[206:209], v[90:93]
	v_mfma_f32_16x16x32_bf16 v[78:81], v[134:137], v[214:217], v[78:81]
	v_mfma_f32_16x16x32_bf16 v[74:77], v[156:159], v[214:217], v[74:77]
	s_setprio 0
	s_setprio 1
	v_mfma_f32_16x16x32_bf16 v[118:121], v[166:169], v[186:189], 0
	v_mfma_f32_16x16x32_bf16 v[114:117], v[174:177], v[186:189], 0
	v_mfma_f32_16x16x32_bf16 v[102:105], v[166:169], v[194:197], 0
	v_mfma_f32_16x16x32_bf16 v[98:101], v[174:177], v[194:197], 0
	v_mfma_f32_16x16x32_bf16 v[86:89], v[166:169], v[202:205], 0
	v_mfma_f32_16x16x32_bf16 v[82:85], v[174:177], v[202:205], 0
	v_mfma_f32_16x16x32_bf16 v[70:73], v[166:169], v[210:213], 0
	v_mfma_f32_16x16x32_bf16 v[66:69], v[174:177], v[210:213], 0
	v_mfma_f32_16x16x32_bf16 v[118:121], v[170:173], v[190:193], v[118:121]
	v_mfma_f32_16x16x32_bf16 v[114:117], v[182:185], v[190:193], v[114:117]
	v_mfma_f32_16x16x32_bf16 v[102:105], v[170:173], v[198:201], v[102:105]
	v_mfma_f32_16x16x32_bf16 v[98:101], v[182:185], v[198:201], v[98:101]
	v_mfma_f32_16x16x32_bf16 v[86:89], v[170:173], v[206:209], v[86:89]
	v_mfma_f32_16x16x32_bf16 v[82:85], v[182:185], v[206:209], v[82:85]
	v_mfma_f32_16x16x32_bf16 v[70:73], v[170:173], v[214:217], v[70:73]
	v_mfma_f32_16x16x32_bf16 v[66:69], v[182:185], v[214:217], v[66:69]
	s_setprio 0
	s_barrier
	s_add_i32 s90, s83, s15
	v_lshl_add_u64 v[178:179], s[60:61], 0, v[138:139]
	s_mov_b32 m0, s90
	ds_read_b128 v[186:189], v163 offset:16384
	ds_read_b128 v[190:193], v163 offset:17408
	ds_read_b128 v[194:197], v163 offset:18432
	ds_read_b128 v[198:201], v163 offset:19456
	ds_read_b128 v[202:205], v163 offset:20480
	ds_read_b128 v[206:209], v163 offset:21504
	ds_read_b128 v[210:213], v163 offset:22528
	ds_read_b128 v[214:217], v163 offset:23552
	global_load_lds_dwordx4 v[178:179], off
	s_add_i32 m0, s90, 0x2000
	s_add_u32 s90, s60, 0x80000
	v_lshl_add_u64 v[178:179], s[60:61], 0, v[140:141]
	s_addc_u32 s91, s61, 0
	s_add_i32 s92, s86, s15
	global_load_lds_dwordx4 v[178:179], off
	v_lshl_add_u64 v[178:179], s[90:91], 0, v[138:139]
	s_mov_b32 m0, s92
	s_nop 0
	global_load_lds_dwordx4 v[178:179], off
	v_lshl_add_u64 v[178:179], s[90:91], 0, v[140:141]
	s_add_i32 m0, s92, 0x2000
	s_nop 0
	global_load_lds_dwordx4 v[178:179], off
	v_lshl_add_u64 v[178:179], s[70:71], 0, v[138:139]
	s_mov_b32 m0, s72
	s_nop 0
	global_load_lds_dwordx4 v[178:179], off
	v_lshl_add_u64 v[178:179], s[70:71], 0, v[140:141]
	s_mov_b32 m0, s73
	s_nop 0
	global_load_lds_dwordx4 v[178:179], off
	s_waitcnt vmcnt(8)
	s_waitcnt lgkmcnt(0)
	s_barrier
; #define PG8_STAGE(bufoff, gbase, voff) do { _Pragma("unroll") for (int _i = 0; _i < 2; ++_i) \
;         __builtin_amdgcn_global_load_lds((const unsigned*)((const char*)(gbase) + (voff)[_i]), (PG8_LAS unsigned*)(lds + (bufoff) + ldsw + _i * 8192), 16, 0, 0); } while (0)
; #define PG8_LDA(dst, b, h) do { _Pragma("unroll") for (int m = 0; m < 4; ++m) _Pragma("unroll") for (int k = 0; k < 2; ++k) dst[m][k] = *(const PG8_LAS bf16x8*)(lds + PG8_SA(b, h) + aoff + m * 2048 + k * 1024); } while (0)
; #define PG8_LDB(dst, b, h) do { _Pragma("unroll") for (int n = 0; n < 2; ++n) _Pragma("unroll") for (int k = 0; k < 2; ++k) dst[n][k] = *(const PG8_LAS bf16x8*)(lds + PG8_SB(b, h) + boff + n * 2048 + k * 1024); } while (0)
; #define PG8_MMA(ai, bj, At, Bt) do { __builtin_amdgcn_s_setprio(1); _Pragma("unroll") for (int m = 0; m < 4; ++m) _Pragma("unroll") for (int n = 0; n < 2; ++n) _Pragma("unroll") for (int k = 0; k < 2; ++k) \
;         acc[ai][bj][m][n] = __builtin_amdgcn_mfma_f32_16x16x32_bf16(Bt[n][k], At[m][k], acc[ai][bj][m][n], 0, 0, 0); __builtin_amdgcn_s_setprio(0); } while (0)
; #define PG8_WAIT_V(n) asm volatile("s_waitcnt vmcnt(" #n ")" ::: "memory")
; #define PG8_WAIT_L(n) asm volatile("s_waitcnt lgkmcnt(" #n ")" ::: "memory")
; #define PG8_BAR __builtin_amdgcn_s_barrier()
; #define PG8_SCHED __builtin_amdgcn_sched_barrier(0)
; template <class Epi, class Sched, bool ALIGN_EPI = false, bool SP2 = false, bool RS = false, bool BPRE = false>
; __device__ __forceinline__ void gemm_phase(PG8_LAS unsigned char* lds, const Gemm g, const Sched& S, const Epi& E, const float* rs_ss = nullptr, PG8_LAS float* rs_tab = nullptr) {
;     ...
;             PG8_WAIT_V(8); PG8_WAIT_L(0); PG8_BAR; PG8_MMA(1, 0, At, B0); PG8_MMA(1, 1, At, B1); PG8_BAR; PG8_SCHED;
;             PG8_LDB(B0, 1, 0); PG8_LDB(B1, 1, 1); PG8_SCHED; PG8_LDA(At, 1, 0); PG8_STAGE(PG8_SA(0, 1), a2 + hstep, voffA);
;             PG8_WAIT_V(8); PG8_WAIT_L(0); PG8_BAR; PG8_MMA(0, 0, At, B0); PG8_MMA(0, 1, At, B1); PG8_BAR; PG8_SCHED;
	s_setprio 1
	s_waitcnt lgkmcnt(0)
	v_mfma_f32_16x16x32_bf16 v[62:65], v[130:133], v[186:189], 0
	v_mfma_f32_16x16x32_bf16 v[58:61], v[152:155], v[186:189], 0
	v_mfma_f32_16x16x32_bf16 v[46:49], v[130:133], v[194:197], 0
	v_mfma_f32_16x16x32_bf16 v[42:45], v[152:155], v[194:197], 0
	v_mfma_f32_16x16x32_bf16 v[30:33], v[130:133], v[202:205], 0
	v_mfma_f32_16x16x32_bf16 v[26:29], v[152:155], v[202:205], 0
	v_mfma_f32_16x16x32_bf16 v[14:17], v[130:133], v[210:213], 0
	v_mfma_f32_16x16x32_bf16 v[10:13], v[152:155], v[210:213], 0
	v_mfma_f32_16x16x32_bf16 v[62:65], v[134:137], v[190:193], v[62:65]
	v_mfma_f32_16x16x32_bf16 v[58:61], v[156:159], v[190:193], v[58:61]
	v_mfma_f32_16x16x32_bf16 v[46:49], v[134:137], v[198:201], v[46:49]
	v_mfma_f32_16x16x32_bf16 v[42:45], v[156:159], v[198:201], v[42:45]
	v_mfma_f32_16x16x32_bf16 v[30:33], v[134:137], v[206:209], v[30:33]
	v_mfma_f32_16x16x32_bf16 v[26:29], v[156:159], v[206:209], v[26:29]
	v_mfma_f32_16x16x32_bf16 v[14:17], v[134:137], v[214:217], v[14:17]
	v_mfma_f32_16x16x32_bf16 v[10:13], v[156:159], v[214:217], v[10:13]
	s_setprio 0
	s_setprio 1
	v_mfma_f32_16x16x32_bf16 v[54:57], v[166:169], v[186:189], 0
	v_mfma_f32_16x16x32_bf16 v[50:53], v[174:177], v[186:189], 0
	v_mfma_f32_16x16x32_bf16 v[38:41], v[166:169], v[194:197], 0
	v_mfma_f32_16x16x32_bf16 v[34:37], v[174:177], v[194:197], 0
	v_mfma_f32_16x16x32_bf16 v[22:25], v[166:169], v[202:205], 0
	v_mfma_f32_16x16x32_bf16 v[18:21], v[174:177], v[202:205], 0
	v_mfma_f32_16x16x32_bf16 v[6:9], v[166:169], v[210:213], 0
	v_mfma_f32_16x16x32_bf16 v[2:5], v[174:177], v[210:213], 0
	v_mfma_f32_16x16x32_bf16 v[54:57], v[170:173], v[190:193], v[54:57]
	v_mfma_f32_16x16x32_bf16 v[50:53], v[182:185], v[190:193], v[50:53]
	v_mfma_f32_16x16x32_bf16 v[38:41], v[170:173], v[198:201], v[38:41]
	v_mfma_f32_16x16x32_bf16 v[34:37], v[182:185], v[198:201], v[34:37]
	v_mfma_f32_16x16x32_bf16 v[22:25], v[170:173], v[206:209], v[22:25]
	v_mfma_f32_16x16x32_bf16 v[18:21], v[182:185], v[206:209], v[18:21]
	v_mfma_f32_16x16x32_bf16 v[6:9], v[170:173], v[214:217], v[6:9]
	v_mfma_f32_16x16x32_bf16 v[2:5], v[182:185], v[214:217], v[2:5]
	s_setprio 0
	s_barrier
	s_add_i32 s90, 0, 0x18000
	v_add_u32_e32 v143, s90, v160
	s_add_i32 s91, 0, 0x1c000
	ds_read_b128 v[130:133], v143
	ds_read_b128 v[134:137], v143 offset:1024
	ds_read_b128 v[152:155], v143 offset:2048
	ds_read_b128 v[156:159], v143 offset:3072
	v_add_u32_e32 v143, s91, v160
	ds_read_b128 v[166:169], v143
	ds_read_b128 v[170:173], v143 offset:1024
	ds_read_b128 v[174:177], v143 offset:2048
	ds_read_b128 v[182:185], v143 offset:3072
	s_add_u32 s70, s70, 0x80000
	s_addc_u32 s71, s71, 0
	s_mov_b32 m0, s74
	v_lshl_add_u64 v[178:179], s[70:71], 0, v[138:139]
	ds_read_b128 v[186:189], v163 offset:32768
	ds_read_b128 v[190:193], v163 offset:33792
	ds_read_b128 v[194:197], v163 offset:34816
	ds_read_b128 v[198:201], v163 offset:35840
	ds_read_b128 v[202:205], v163 offset:36864
	ds_read_b128 v[206:209], v163 offset:37888
	ds_read_b128 v[210:213], v163 offset:38912
	ds_read_b128 v[214:217], v163 offset:39936
	global_load_lds_dwordx4 v[178:179], off
	v_lshl_add_u64 v[178:179], s[70:71], 0, v[140:141]
	s_mov_b32 m0, s75
	s_nop 0
	global_load_lds_dwordx4 v[178:179], off
	s_waitcnt vmcnt(8)
	s_waitcnt lgkmcnt(0)
	s_barrier
	s_setprio 1
	s_waitcnt lgkmcnt(0)
	v_mfma_f32_16x16x32_bf16 v[126:129], v[130:133], v[186:189], v[126:129]
	v_mfma_f32_16x16x32_bf16 v[122:125], v[152:155], v[186:189], v[122:125]
	v_mfma_f32_16x16x32_bf16 v[110:113], v[130:133], v[194:197], v[110:113]
	v_mfma_f32_16x16x32_bf16 v[106:109], v[152:155], v[194:197], v[106:109]
	v_mfma_f32_16x16x32_bf16 v[94:97], v[130:133], v[202:205], v[94:97]
	v_mfma_f32_16x16x32_bf16 v[90:93], v[152:155], v[202:205], v[90:93]
	v_mfma_f32_16x16x32_bf16 v[78:81], v[130:133], v[210:213], v[78:81]
	v_mfma_f32_16x16x32_bf16 v[74:77], v[152:155], v[210:213], v[74:77]
	v_mfma_f32_16x16x32_bf16 v[126:129], v[134:137], v[190:193], v[126:129]
	v_mfma_f32_16x16x32_bf16 v[122:125], v[156:159], v[190:193], v[122:125]
	v_mfma_f32_16x16x32_bf16 v[110:113], v[134:137], v[198:201], v[110:113]
	v_mfma_f32_16x16x32_bf16 v[106:109], v[156:159], v[198:201], v[106:109]
	v_mfma_f32_16x16x32_bf16 v[94:97], v[134:137], v[206:209], v[94:97]
	v_mfma_f32_16x16x32_bf16 v[90:93], v[156:159], v[206:209], v[90:93]
	v_mfma_f32_16x16x32_bf16 v[78:81], v[134:137], v[214:217], v[78:81]
	v_mfma_f32_16x16x32_bf16 v[74:77], v[156:159], v[214:217], v[74:77]
	s_setprio 0
	s_setprio 1
	v_mfma_f32_16x16x32_bf16 v[118:121], v[166:169], v[186:189], v[118:121]
	v_mfma_f32_16x16x32_bf16 v[114:117], v[174:177], v[186:189], v[114:117]
	v_mfma_f32_16x16x32_bf16 v[102:105], v[166:169], v[194:197], v[102:105]
	v_mfma_f32_16x16x32_bf16 v[98:101], v[174:177], v[194:197], v[98:101]
	v_mfma_f32_16x16x32_bf16 v[86:89], v[166:169], v[202:205], v[86:89]
	v_mfma_f32_16x16x32_bf16 v[82:85], v[174:177], v[202:205], v[82:85]
	v_mfma_f32_16x16x32_bf16 v[70:73], v[166:169], v[210:213], v[70:73]
	v_mfma_f32_16x16x32_bf16 v[66:69], v[174:177], v[210:213], v[66:69]
	v_mfma_f32_16x16x32_bf16 v[118:121], v[170:173], v[190:193], v[118:121]
	v_mfma_f32_16x16x32_bf16 v[114:117], v[182:185], v[190:193], v[114:117]
	v_mfma_f32_16x16x32_bf16 v[102:105], v[170:173], v[198:201], v[102:105]
	v_mfma_f32_16x16x32_bf16 v[98:101], v[182:185], v[198:201], v[98:101]
	v_mfma_f32_16x16x32_bf16 v[86:89], v[170:173], v[206:209], v[86:89]
	v_mfma_f32_16x16x32_bf16 v[82:85], v[182:185], v[206:209], v[82:85]
	v_mfma_f32_16x16x32_bf16 v[70:73], v[170:173], v[214:217], v[70:73]
	v_mfma_f32_16x16x32_bf16 v[66:69], v[182:185], v[214:217], v[66:69]
	s_setprio 0
	s_barrier
; #define PG8_STAGE(bufoff, gbase, voff) do { _Pragma("unroll") for (int _i = 0; _i < 2; ++_i) \
;         __builtin_amdgcn_global_load_lds((const unsigned*)((const char*)(gbase) + (voff)[_i]), (PG8_LAS unsigned*)(lds + (bufoff) + ldsw + _i * 8192), 16, 0, 0); } while (0)
; #define PG8_LDA(dst, b, h) do { _Pragma("unroll") for (int m = 0; m < 4; ++m) _Pragma("unroll") for (int k = 0; k < 2; ++k) dst[m][k] = *(const PG8_LAS bf16x8*)(lds + PG8_SA(b, h) + aoff + m * 2048 + k * 1024); } while (0)
; #define PG8_MMA(ai, bj, At, Bt) do { __builtin_amdgcn_s_setprio(1); _Pragma("unroll") for (int m = 0; m < 4; ++m) _Pragma("unroll") for (int n = 0; n < 2; ++n) _Pragma("unroll") for (int k = 0; k < 2; ++k) \
;         acc[ai][bj][m][n] = __builtin_amdgcn_mfma_f32_16x16x32_bf16(Bt[n][k], At[m][k], acc[ai][bj][m][n], 0, 0, 0); __builtin_amdgcn_s_setprio(0); } while (0)
; #define PG8_WAIT_V(n) asm volatile("s_waitcnt vmcnt(" #n ")" ::: "memory")
; #define PG8_WAIT_L(n) asm volatile("s_waitcnt lgkmcnt(" #n ")" ::: "memory")
; #define PG8_BAR __builtin_amdgcn_s_barrier()
; #define PG8_SCHED __builtin_amdgcn_sched_barrier(0)
; template <class Epi, class Sched, bool ALIGN_EPI = false, bool SP2 = false, bool RS = false, bool BPRE = false>
; __device__ __forceinline__ void gemm_phase(PG8_LAS unsigned char* lds, const Gemm g, const Sched& S, const Epi& E, const float* rs_ss = nullptr, PG8_LAS float* rs_tab = nullptr) {
;     ...
;             PG8_LDA(At, 1, 1); PG8_STAGE(PG8_SB(1, 0), b3, voffB); PG8_STAGE(PG8_SB(1, 1), b3 + hstep, voffB); PG8_STAGE(PG8_SA(1, 0), a3, voffA);
;             PG8_WAIT_V(8); PG8_WAIT_L(0); PG8_BAR; PG8_MMA(1, 0, At, B0); PG8_MMA(1, 1, At, B1); PG8_BAR; PG8_SCHED;
	s_add_u32 s70, s60, 0x4000
	s_addc_u32 s71, s61, 0
	s_add_i32 s90, s90, s15
	v_lshl_add_u64 v[178:179], s[70:71], 0, v[138:139]
	s_mov_b32 m0, s90
	ds_read_b128 v[186:189], v163 offset:49152
	ds_read_b128 v[190:193], v163 offset:50176
	ds_read_b128 v[194:197], v163 offset:51200
	ds_read_b128 v[198:201], v163 offset:52224
	ds_read_b128 v[202:205], v163 offset:53248
	ds_read_b128 v[206:209], v163 offset:54272
	ds_read_b128 v[210:213], v163 offset:55296
	ds_read_b128 v[214:217], v163 offset:56320
	global_load_lds_dwordx4 v[178:179], off
	s_add_i32 m0, s90, 0x2000
	s_add_u32 s60, s60, 0x84000
	v_lshl_add_u64 v[178:179], s[70:71], 0, v[140:141]
	s_addc_u32 s61, s61, 0
	s_add_i32 s70, s91, s15
	global_load_lds_dwordx4 v[178:179], off
	v_lshl_add_u64 v[178:179], s[60:61], 0, v[138:139]
	s_mov_b32 m0, s70
	s_nop 0
	global_load_lds_dwordx4 v[178:179], off
	v_lshl_add_u64 v[178:179], s[60:61], 0, v[140:141]
	s_add_i32 m0, s70, 0x2000
	s_nop 0
	global_load_lds_dwordx4 v[178:179], off
	v_lshl_add_u64 v[178:179], s[58:59], 0, v[138:139]
	s_mov_b32 m0, s79
	s_nop 0
	global_load_lds_dwordx4 v[178:179], off
	v_lshl_add_u64 v[178:179], s[58:59], 0, v[140:141]
	s_mov_b32 m0, s80
	s_nop 0
	global_load_lds_dwordx4 v[178:179], off
	s_waitcnt vmcnt(8)
	s_waitcnt lgkmcnt(0)
	s_barrier
	s_setprio 1
	s_waitcnt lgkmcnt(0)
	v_mfma_f32_16x16x32_bf16 v[62:65], v[130:133], v[186:189], v[62:65]
	v_mfma_f32_16x16x32_bf16 v[58:61], v[152:155], v[186:189], v[58:61]
	v_mfma_f32_16x16x32_bf16 v[46:49], v[130:133], v[194:197], v[46:49]
	v_mfma_f32_16x16x32_bf16 v[42:45], v[152:155], v[194:197], v[42:45]
	v_mfma_f32_16x16x32_bf16 v[30:33], v[130:133], v[202:205], v[30:33]
	v_mfma_f32_16x16x32_bf16 v[26:29], v[152:155], v[202:205], v[26:29]
	v_mfma_f32_16x16x32_bf16 v[14:17], v[130:133], v[210:213], v[14:17]
	v_mfma_f32_16x16x32_bf16 v[10:13], v[152:155], v[210:213], v[10:13]
	v_mfma_f32_16x16x32_bf16 v[62:65], v[134:137], v[190:193], v[62:65]
	v_mfma_f32_16x16x32_bf16 v[58:61], v[156:159], v[190:193], v[58:61]
	v_mfma_f32_16x16x32_bf16 v[46:49], v[134:137], v[198:201], v[46:49]
	v_mfma_f32_16x16x32_bf16 v[42:45], v[156:159], v[198:201], v[42:45]
	v_mfma_f32_16x16x32_bf16 v[30:33], v[134:137], v[206:209], v[30:33]
	v_mfma_f32_16x16x32_bf16 v[26:29], v[156:159], v[206:209], v[26:29]
	v_mfma_f32_16x16x32_bf16 v[14:17], v[134:137], v[214:217], v[14:17]
	v_mfma_f32_16x16x32_bf16 v[10:13], v[156:159], v[214:217], v[10:13]
	s_setprio 0
	s_setprio 1
	v_mfma_f32_16x16x32_bf16 v[54:57], v[166:169], v[186:189], v[54:57]
	v_mfma_f32_16x16x32_bf16 v[50:53], v[174:177], v[186:189], v[50:53]
	v_mfma_f32_16x16x32_bf16 v[38:41], v[166:169], v[194:197], v[38:41]
	v_mfma_f32_16x16x32_bf16 v[34:37], v[174:177], v[194:197], v[34:37]
	v_mfma_f32_16x16x32_bf16 v[22:25], v[166:169], v[202:205], v[22:25]
	v_mfma_f32_16x16x32_bf16 v[18:21], v[174:177], v[202:205], v[18:21]
	v_mfma_f32_16x16x32_bf16 v[6:9], v[166:169], v[210:213], v[6:9]
	v_mfma_f32_16x16x32_bf16 v[2:5], v[174:177], v[210:213], v[2:5]
	v_mfma_f32_16x16x32_bf16 v[54:57], v[170:173], v[190:193], v[54:57]
	v_mfma_f32_16x16x32_bf16 v[50:53], v[182:185], v[190:193], v[50:53]
	v_mfma_f32_16x16x32_bf16 v[38:41], v[170:173], v[198:201], v[38:41]
	v_mfma_f32_16x16x32_bf16 v[34:37], v[182:185], v[198:201], v[34:37]
	v_mfma_f32_16x16x32_bf16 v[22:25], v[170:173], v[206:209], v[22:25]
	v_mfma_f32_16x16x32_bf16 v[18:21], v[182:185], v[206:209], v[18:21]
	v_mfma_f32_16x16x32_bf16 v[6:9], v[170:173], v[214:217], v[6:9]
	v_mfma_f32_16x16x32_bf16 v[2:5], v[182:185], v[214:217], v[2:5]
	s_setprio 0
	s_barrier
	s_add_i32 s89, s89, 2
	s_add_u32 s56, s56, 0x8000
	s_addc_u32 s57, s57, 0
	s_add_u32 s87, s87, 0x8000
	s_addc_u32 s88, s88, 0

; #define PG8_STAGE(bufoff, gbase, voff) do { _Pragma("unroll") for (int _i = 0; _i < 2; ++_i) \
;         __builtin_amdgcn_global_load_lds((const unsigned*)((const char*)(gbase) + (voff)[_i]), (PG8_LAS unsigned*)(lds + (bufoff) + ldsw + _i * 8192), 16, 0, 0); } while (0)
; #define PG8_LDA(dst, b, h) do { _Pragma("unroll") for (int m = 0; m < 4; ++m) _Pragma("unroll") for (int k = 0; k < 2; ++k) dst[m][k] = *(const PG8_LAS bf16x8*)(lds + PG8_SA(b, h) + aoff + m * 2048 + k * 1024); } while (0)
; #define PG8_LDB(dst, b, h) do { _Pragma("unroll") for (int n = 0; n < 2; ++n) _Pragma("unroll") for (int k = 0; k < 2; ++k) dst[n][k] = *(const PG8_LAS bf16x8*)(lds + PG8_SB(b, h) + boff + n * 2048 + k * 1024); } while (0)
; #define PG8_SCHED __builtin_amdgcn_sched_barrier(0)
; #define LAS __attribute__((address_space(3)))
; template <class Epi, class Sched, bool ALIGN_EPI = false, bool SP2 = false, bool RS = false, bool BPRE = false>
; __device__ __forceinline__ void gemm_phase(PG8_LAS unsigned char* lds, const Gemm g, const Sched& S, const Epi& E, const float* rs_ss = nullptr, PG8_LAS float* rs_tab = nullptr) {
;     ...
;             PG8_LDB(B0, 0, 0); PG8_LDB(B1, 0, 1); PG8_SCHED; PG8_LDA(At, 0, 0); PG8_STAGE(PG8_SA(1, 1), a1 + hstep, voffA);
;     __device__ __forceinline__ void operator()(const f32x4 (&acc)[2][2][4][2], const pg8::Unit& u, int wr, int wc, int fr, int fq, const LAS float* tab) const {
;         int kind = 0, pm = u.pm, pn = u.pn, ldc = INW; bf16_t* base = O;
;         if (mode == 0) { const int seg = pn >> 2; kind = (seg == 1 || seg == 4 || seg == 6) ? 1 : (seg == 5 ? 2 : (seg == 3 ? 3 : 0)); }
.LBB0_199:
	ds_read_b128 v[130:133], v161
	ds_read_b128 v[134:137], v161 offset:1024
	ds_read_b128 v[152:155], v161 offset:2048
	ds_read_b128 v[156:159], v161 offset:3072
	ds_read_b128 v[166:169], v162
	ds_read_b128 v[170:173], v162 offset:1024
	ds_read_b128 v[174:177], v162 offset:2048
	ds_read_b128 v[182:185], v162 offset:3072
	ds_read_b128 v[186:189], v163
	ds_read_b128 v[190:193], v163 offset:1024
	ds_read_b128 v[194:197], v163 offset:2048
	ds_read_b128 v[198:201], v163 offset:3072
	ds_read_b128 v[202:205], v163 offset:4096
	ds_read_b128 v[206:209], v163 offset:5120
	ds_read_b128 v[210:213], v163 offset:6144
	ds_read_b128 v[214:217], v163 offset:7168
	v_and_b32_e32 v218, 15, v164
	v_bfe_u32 v219, v164, 4, 2
	v_lshlrev_b32_e32 v218, 6, v218
	v_lshl_or_b32 v218, v219, 4, v218
	s_and_b32 s93, s33, 3
	s_lshl_b32 s94, s93, 10
	v_or_b32_e32 v218, s94, v218
	v_and_b32_e32 v219, 15, v164
	v_lshlrev_b32_e32 v219, 7, v219
	s_lshl_b32 s94, s4, 23
	s_lshl_b32 s95, s46, 4
	s_lshr_b32 s98, s33, 2
	s_lshl_b32 s99, s98, 2
	s_add_i32 s95, s95, s99
	s_lshl_b32 s95, s95, 13
	s_add_u32 s94, s94, s95
	s_add_u32 s96, s36, s94
	s_addc_u32 s97, s37, 0
	s_lshr_b32 s94, s4, 2
	s_cmp_eq_u32 s94, 1
	s_cbranch_scc1 .Lepi_silu
	s_cmp_eq_u32 s94, 4
	s_cbranch_scc1 .Lepi_silu
	s_cmp_eq_u32 s94, 6
	s_cbranch_scc1 .Lepi_silu
	s_cmp_eq_u32 s94, 5
	s_cbranch_scc1 .Lepi_scale
	s_cmp_eq_u32 s94, 3
	s_cbranch_scc1 .Lepi_stats
